# v30 plus dense layer-0 loop: counter increment moved from behind the loop-back barrier to in front of it (after the exit branch), prologue pre-increments
# speedup vs baseline: 1.0074x; 1.0029x over previous
; __device__ __forceinline__ int v_st_ns(int k, int c) { return ((k >> 3) * 2 + (c >> 5)) * 512 + ((k & 7) * 32 + (c & 31)) * 2; }
; __device__ __forceinline__ int v_rd_base(int lane) { return ((lane & 3) << 3) | (((lane >> 2) & 3) << 6) | (((lane >> 4) & 1) << 5) | (((lane >> 5) & 1) << 8); }
; #define SWRITE(b, i) do { *(bf16x8*)(V_lds + (b) * SHM_V + vst0) = st_[i].vs; *(bf16x8*)(K_lds + (b) * SHM_K + kst0) = st_[i].ks; \
;     if (DQ == 96) { if (tid < 256) *(bf16x8*)(K_lds + (b) * SHM_K + kst2) = st_[i].kr; } } while (0)
; template <int DQ, bool WIN, int LDQ, int LDK> ...
;     ...
;     const bf16_t* Qw = Qb + (size_t)(wid * 32 + r32) * LDQ + hi * 8;
; #pragma unroll
;     for (int d0 = 0; d0 < ND; ++d0) qr[d0] = *reinterpret_cast<const bf16x8*>(Qw + d0 * 16);
;     const int sr = tid >> 3, sc = (tid & 7) * 8, vst0 = v_st_ns(sr, sc);
;     const int kst0 = sr * KROW + sc * 2;
;     const int sr2 = (tid & 255) >> 2, sc2 = (tid & 3) * 8; const int kst2 = sr2 * KROW + 128 + sc2 * 2;
;     const int vb0 = (int)(uintptr_t)V_lds + v_rd_base(lane);
;     const int qrow = q0 + wid * 32 + r32;
;     struct { bf16x8 vs, ks, kr; } st_[2];
;     ...
;     f32x16 pA0, pA1, pB0, pB1; bf16x8 pa0, pa1, pa2, pa3;
;     auto finish = [&](f32x16& p0, f32x16& p1) {
;         exp16(p1);
;         pack_p_ns(p0, p1, pa0, pa1, pa2, pa3);
;     };
;     auto pv = [&](int vb) {
;         pv_d0(o, vb, pa0, pa1, pa2, pa3);
;     };
;     auto lsum_upd = [&]() {
;         lsum = __builtin_amdgcn_mfma_f32_32x32x16_bf16(pa0, ones8, lsum, 0, 0, 0);
;         lsum = __builtin_amdgcn_mfma_f32_32x32x16_bf16(pa1, ones8, lsum, 0, 0, 0);
;         lsum = __builtin_amdgcn_mfma_f32_32x32x16_bf16(pa2, ones8, lsum, 0, 0, 0);
;         lsum = __builtin_amdgcn_mfma_f32_32x32x16_bf16(pa3, ones8, lsum, 0, 0, 0);
;     };
;     constexpr int SE = 0, SO = 1;
;     SLOAD(SE, KBASE(0)); SLOAD(SO, KBASE(1));
;     SWAIT(); SWRITE(0, SE); __syncthreads();
;     qkt<DQ>(pA0, pA1, K_lds, qr, zero16, r32, hi);
;     if (WIN) win_mask(pA0, pA1, qrow - KBASE(0), hi);
;     { const float pm = row_max32(pA0, pA1); m_ref = (pm > -1e37f) ? pm : 0.f;
; #pragma unroll
;       for (int r = 0; r < 16; ++r) { minit[r] = -m_ref; pA0[r] -= m_ref; pA1[r] -= m_ref; } }
;     exp16(pA0);
;     if (2 < NT) SLOAD(SE, KBASE(2));
;     SWAIT(); SWRITE(1, SO); __syncthreads();
.LBB0_491:
	s_or_b64 exec, exec, s[0:1]
	s_or_b32 s10, s65, s63
	s_mul_i32 s0, s10, 0xc00
	s_add_u32 s0, s69, s0
	s_addc_u32 s1, s70, 0
	s_lshl_b32 s11, s64, 6
	s_lshl_b32 s4, s64, 7
	s_add_u32 s6, s0, s4
	s_addc_u32 s7, s1, 0
	s_add_u32 s0, s69, s62
	s_addc_u32 s1, s70, 0
	s_lshl_b32 s4, s37, 7
	s_add_u32 s4, s0, s4
	v_ashrrev_i32_e32 v35, 3, v34
	v_lshlrev_b32_e32 v12, 3, v34
	s_addc_u32 s5, s1, 0
	v_and_b32_e32 v82, 56, v12
	v_mad_i64_i32 v[2:3], s[0:1], v35, s83, 0
	v_or_b32_e32 v2, v2, v82
	v_lshl_add_u64 v[6:7], v[2:3], 1, s[4:5]
	global_load_dwordx4 v[2:5], v[6:7], off offset:1280
	s_nop 0
	global_load_dwordx4 v[6:9], v[6:7], off offset:1024
	s_ashr_i32 s20, s20, 1
	v_mov_b32_e32 v10, s20
	v_bfe_u32 v1, v34, 5, 1
	v_bfi_b32 v13, s79, v10, v34
	v_mov_b64_e32 v[10:11], s[6:7]
	v_mad_i64_i32 v[10:11], s[0:1], v13, s78, v[10:11]
	v_lshlrev_b32_e32 v146, 4, v1
	v_lshl_add_u64 v[10:11], v[10:11], 0, v[146:147]
	global_load_dwordx4 v[126:129], v[10:11], off
	global_load_dwordx4 v[122:125], v[10:11], off offset:32
	global_load_dwordx4 v[118:121], v[10:11], off offset:64
	global_load_dwordx4 v[114:117], v[10:11], off offset:96
	v_bfe_u32 v14, v12, 5, 1
	v_lshlrev_b32_e32 v15, 5, v35
	v_and_b32_e32 v12, 24, v12
	v_lshrrev_b32_e32 v13, 5, v34
	v_add_u32_e32 v17, 64, v35
	v_and_or_b32 v12, v15, s81, v12
	v_and_b32_e32 v150, 31, v34
	v_and_or_b32 v13, v13, s80, v14
	v_mad_i64_i32 v[10:11], s[0:1], v17, s83, 0
	v_lshlrev_b32_e32 v12, 1, v12
	v_mul_lo_u32 v16, v35, s82
	s_waitcnt vmcnt(0)
	v_mad_u32_u24 v18, v150, s82, 0
	v_or_b32_e32 v10, v10, v82
	v_lshl_or_b32 v12, v13, 9, v12
	v_lshl_add_u32 v14, v82, 1, v16
	v_add_u32_e32 v156, v18, v146
	v_add_u32_e32 v158, 0, v12
	v_lshl_add_u64 v[10:11], v[10:11], 1, s[4:5]
	v_add_u32_e32 v157, 0, v14
	global_load_dwordx4 v[36:39], v[10:11], off offset:1280
	global_load_dwordx4 v[40:43], v[10:11], off offset:1024
	s_waitcnt vmcnt(2)
	v_and_b32_e32 v151, 63, v34
	s_andn2_b32 s20, s20, 31
	s_cmp_lg_u32 0, -1
	s_cselect_b32 s22, 0, 0
	s_mov_b32 s21, 1
	ds_write_b128 v158, v[2:5]
	ds_write_b128 v157, v[6:9] offset:16384
	s_waitcnt lgkmcnt(0)
	s_barrier
	ds_read_b128 v[2:5], v156 offset:16384
	ds_read_b128 v[44:47], v156 offset:16416
	s_waitcnt lgkmcnt(1)
	v_mfma_f32_32x32x16_bf16 v[18:33], v[2:5], v[126:129], 0
	ds_read_b128 v[2:5], v156 offset:20992
	ds_read_b128 v[48:51], v156 offset:21024
	s_waitcnt lgkmcnt(1)
	v_mfma_f32_32x32x16_bf16 v[2:17], v[2:5], v[126:129], 0
	v_mfma_f32_32x32x16_bf16 v[18:33], v[44:47], v[122:125], v[18:33]
	s_waitcnt lgkmcnt(0)
	v_mfma_f32_32x32x16_bf16 v[2:17], v[48:51], v[122:125], v[2:17]
	ds_read_b128 v[44:47], v156 offset:16448
	ds_read_b128 v[48:51], v156 offset:16480
	s_waitcnt lgkmcnt(1)
	v_mfma_f32_32x32x16_bf16 v[18:33], v[44:47], v[118:121], v[18:33]
	ds_read_b128 v[44:47], v156 offset:21056
	ds_read_b128 v[52:55], v156 offset:21088
	s_waitcnt lgkmcnt(2)
	v_mfma_f32_32x32x16_bf16 v[18:33], v[48:51], v[114:117], v[18:33]
	s_waitcnt lgkmcnt(1)
	v_mfma_f32_32x32x16_bf16 v[2:17], v[44:47], v[118:121], v[2:17]
	v_lshlrev_b32_e32 v44, 4, v34
	v_lshlrev_b32_e32 v45, 1, v34
	v_lshlrev_b32_e32 v46, 3, v151
	v_and_b32_e32 v44, 0xc0, v44
	v_and_b32_e32 v45, 32, v45
	v_and_or_b32 v44, v46, 24, v44
	v_and_b32_e32 v46, 0x100, v46
	v_or3_b32 v44, v44, v45, v46
	s_nop 1
	v_max_f32_e32 v45, v19, v19
	v_max_f32_e32 v46, v18, v18
	s_waitcnt lgkmcnt(0)
	v_mfma_f32_32x32x16_bf16 v[2:17], v[52:55], v[114:117], v[2:17]
	v_max_f32_e32 v45, v46, v45
	v_max3_f32 v45, v45, v20, v21
	v_max3_f32 v45, v45, v22, v23
	v_max3_f32 v45, v45, v24, v25
	v_max3_f32 v45, v45, v26, v27
	v_max3_f32 v45, v45, v28, v29
	v_max3_f32 v45, v45, v30, v31
	v_max3_f32 v45, v45, v32, v33
	s_nop 3
	v_max3_f32 v45, v45, v2, v3
	v_max3_f32 v45, v45, v4, v5
	v_max3_f32 v45, v45, v6, v7
	v_max3_f32 v45, v45, v8, v9
	v_max3_f32 v45, v45, v10, v11
	v_max3_f32 v45, v45, v12, v13
	v_max3_f32 v45, v45, v14, v15
	v_max3_f32 v45, v45, v16, v17
	v_mov_b32_e32 v46, v45
	s_nop 1
	v_permlane32_swap_b32_e32 v45, v46
	v_max_f32_e32 v46, v46, v46
	v_max_f32_e32 v45, v45, v45
	v_max_f32_e32 v45, v45, v46
	v_cmp_lt_f32_e32 vcc, s85, v45
	v_add_u32_e32 v159, s22, v44
	s_addk_i32 s22, 0x2000
	v_cndmask_b32_e32 v45, 0, v45, vcc
	v_sub_f32_e32 v66, v2, v45
	v_add_u32_e32 v2, 0x80, v35
	v_sub_f32_e32 v67, v3, v45
	v_mad_i64_i32 v[2:3], s[0:1], v2, s83, 0
	v_or_b32_e32 v2, v2, v82
	v_lshl_add_u64 v[2:3], v[2:3], 1, s[4:5]
	global_load_dwordx4 v[130:133], v[2:3], off offset:1024
	global_load_dwordx4 v[134:137], v[2:3], off offset:1280
	s_add_u32 s0, s33, s67
	s_addc_u32 s1, 0, 0
	v_sub_f32_e32 v18, v18, v45
	v_sub_f32_e32 v19, v19, v45
	v_sub_f32_e32 v20, v20, v45
	v_sub_f32_e32 v21, v21, v45
	v_sub_f32_e32 v22, v22, v45
	v_sub_f32_e32 v23, v23, v45
	v_sub_f32_e32 v24, v24, v45
	v_sub_f32_e32 v25, v25, v45
	v_sub_f32_e32 v26, v26, v45
	v_sub_f32_e32 v27, v27, v45
	v_sub_f32_e32 v28, v28, v45
	v_sub_f32_e32 v29, v29, v45
	v_sub_f32_e32 v30, v30, v45
	v_sub_f32_e32 v31, v31, v45
	v_sub_f32_e32 v32, v32, v45
	v_sub_f32_e32 v33, v33, v45
	v_sub_f32_e32 v68, v4, v45
	v_mov_b64_e32 v[2:3], s[0:1]
	v_and_b32_e32 v4, 7, v34
	v_exp_f32_e32 v138, v18
	v_exp_f32_e32 v139, v19
	v_exp_f32_e32 v162, v20
	v_exp_f32_e32 v165, v21
	v_exp_f32_e32 v163, v22
	v_exp_f32_e32 v166, v23
	v_exp_f32_e32 v164, v24
	v_exp_f32_e32 v167, v25
	v_exp_f32_e32 v140, v26
	v_exp_f32_e32 v144, v27
	v_exp_f32_e32 v141, v28
	v_exp_f32_e32 v145, v29
	v_exp_f32_e32 v142, v30
	v_exp_f32_e32 v160, v31
	v_exp_f32_e32 v143, v32
	v_exp_f32_e32 v161, v33
	v_mad_i64_i32 v[2:3], s[0:1], v35, s78, v[2:3]
	v_lshlrev_b32_e32 v146, 4, v4
	s_waitcnt vmcnt(2)
; #define SLOAD(i, k0) do { st_[i].vs = *reinterpret_cast<const bf16x8*>(&Vh[(size_t)((k0) + sr) * LDK + sc]); \
;     st_[i].ks = *reinterpret_cast<const bf16x8*>(&Kh[(size_t)((k0) + sr) * LDK + sc]); \
;     if (DQ == 96) st_[i].kr = *reinterpret_cast<const bf16x8*>(&Kr[(size_t)((k0) + sr2) * 32 + sc2]); } while (0)
; #define SWRITE(b, i) do { *(bf16x8*)(V_lds + (b) * SHM_V + vst0) = st_[i].vs; *(bf16x8*)(K_lds + (b) * SHM_K + kst0) = st_[i].ks; \
;     if (DQ == 96) { if (tid < 256) *(bf16x8*)(K_lds + (b) * SHM_K + kst2) = st_[i].kr; } } while (0)
; #define SWAIT() do { if (DQ == 96) asm volatile("s_waitcnt vmcnt(3)" ::: "memory"); else asm volatile("s_waitcnt vmcnt(2)" ::: "memory"); } while (0)
; #define SLOAD(i, k0) do { st_[i].vs = *reinterpret_cast<const bf16x8*>(&Vh[(size_t)((k0) + sr) * LDK + sc]); \
;     st_[i].ks = *reinterpret_cast<const bf16x8*>(&Kh[(size_t)((k0) + sr) * LDK + sc]); \
;     if (DQ == 96) st_[i].kr = *reinterpret_cast<const bf16x8*>(&Kr[(size_t)((k0) + sr2) * 32 + sc2]); } while (0)
; #define SWRITE(b, i) do { *(bf16x8*)(V_lds + (b) * SHM_V + vst0) = st_[i].vs; *(bf16x8*)(K_lds + (b) * SHM_K + kst0) = st_[i].ks; \
;     if (DQ == 96) { if (tid < 256) *(bf16x8*)(K_lds + (b) * SHM_K + kst2) = st_[i].kr; } } while (0)
; #define SWAIT() do { if (DQ == 96) asm volatile("s_waitcnt vmcnt(3)" ::: "memory"); else asm volatile("s_waitcnt vmcnt(2)" ::: "memory"); } while (0)
; template <int DQ, bool WIN, int LDQ, int LDK> ...
;     ...
;     { const float pm = row_max32(pA0, pA1); m_ref = (pm > -1e37f) ? pm : 0.f;
; #pragma unroll
;       for (int r = 0; r < 16; ++r) { minit[r] = -m_ref; pA0[r] -= m_ref; pA1[r] -= m_ref; } }
;     exp16(pA0);
;     if (2 < NT) SLOAD(SE, KBASE(2));
;     SWAIT(); SWRITE(1, SO); __syncthreads();
;     ...
;         pv(vb0 + SHM_V);
;         __syncthreads(); SWAIT(); SWRITE(1, SO);
;         lsum_upd();
;         if (WIN) win_mask(pA0, pA1, qrow - KBASE(j + 1), hi);
;         exp16(pA0);
;         __syncthreads();
	v_lshl_add_u64 v[2:3], v[2:3], 0, v[146:147]
	v_xor_b32_e32 v50, 0x80000000, v45
	v_lshl_add_u64 v[148:149], s[16:17], 0, v[2:3]
	v_mov_b32_e32 v2, 0
	v_sub_f32_e32 v81, v17, v45
	v_sub_f32_e32 v80, v16, v45
	v_sub_f32_e32 v79, v15, v45
	v_sub_f32_e32 v78, v14, v45
	v_sub_f32_e32 v77, v13, v45
	v_sub_f32_e32 v76, v12, v45
	v_sub_f32_e32 v75, v11, v45
	v_sub_f32_e32 v74, v10, v45
	v_sub_f32_e32 v73, v9, v45
	v_mov_b32_e32 v51, v50
	v_mov_b32_e32 v52, v50
	v_mov_b32_e32 v53, v50
	v_mov_b32_e32 v54, v50
	v_mov_b32_e32 v55, v50
	v_mov_b32_e32 v56, v50
	v_mov_b32_e32 v57, v50
	v_mov_b32_e32 v58, v50
	v_mov_b32_e32 v59, v50
	v_mov_b32_e32 v60, v50
	v_mov_b32_e32 v61, v50
	v_mov_b32_e32 v62, v50
	v_mov_b32_e32 v63, v50
	v_mov_b32_e32 v64, v50
	v_mov_b32_e32 v65, v50
	v_sub_f32_e32 v72, v8, v45
	v_sub_f32_e32 v71, v7, v45
	v_sub_f32_e32 v70, v6, v45
	v_sub_f32_e32 v69, v5, v45
	s_waitcnt vmcnt(3)
	ds_write_b128 v158, v[36:39] offset:8192
	s_waitcnt vmcnt(2)
	ds_write_b128 v157, v[40:43] offset:25600
	v_add_u32_e32 v155, s22, v44
	v_mov_b32_e32 v3, v2
	v_mov_b32_e32 v4, v2
	v_mov_b32_e32 v5, v2
	v_mov_b32_e32 v6, v2
	v_mov_b32_e32 v7, v2
	v_mov_b32_e32 v8, v2
	v_mov_b32_e32 v9, v2
	v_mov_b32_e32 v10, v2
	v_mov_b32_e32 v11, v2
	v_mov_b32_e32 v12, v2
	v_mov_b32_e32 v13, v2
	v_mov_b32_e32 v14, v2
	v_mov_b32_e32 v15, v2
	v_mov_b32_e32 v16, v2
	v_mov_b32_e32 v17, v2
	v_mov_b32_e32 v18, v2
	v_mov_b32_e32 v19, v2
	v_mov_b32_e32 v20, v2
	v_mov_b32_e32 v21, v2
	v_mov_b32_e32 v22, v2
	v_mov_b32_e32 v23, v2
	v_mov_b32_e32 v24, v2
	v_mov_b32_e32 v25, v2
	v_mov_b32_e32 v26, v2
	v_mov_b32_e32 v27, v2
	v_mov_b32_e32 v28, v2
	v_mov_b32_e32 v29, v2
	v_mov_b32_e32 v30, v2
	v_mov_b32_e32 v31, v2
	v_mov_b32_e32 v32, v2
	v_mov_b32_e32 v33, v2
	v_mov_b32_e32 v34, v2
	v_mov_b32_e32 v35, v2
	v_mov_b32_e32 v36, v2
	v_mov_b32_e32 v37, v2
	v_lshrrev_b32_e32 v38, 4, v151
	v_xor_b32_e32 v38, v38, v151
	v_not_b32_e32 v38, v38
	v_bfe_i32 v38, v38, 0, 1
	v_and_b32_e32 v38, 0x3f803f80, v38
	v_mov_b32_e32 v39, v38
	v_mov_b32_e32 v40, v38
	v_mov_b32_e32 v41, v38
	v_mov_b32_e32 v42, v2
	v_mov_b32_e32 v43, v2
	v_mov_b32_e32 v44, v2
	v_mov_b32_e32 v45, v2
	v_mov_b32_e32 v46, v2
	v_mov_b32_e32 v47, v2
	v_mov_b32_e32 v48, v2
	v_mov_b32_e32 v49, v2
	v_xor_b32_e32 v158, 0xc000, v158
	s_waitcnt lgkmcnt(0)
	s_barrier
	s_branch .LBB0_493
.LBB0_492:
	ds_read_b64_tr_b16 v[168:169], v155 offset:0x1000
	ds_read_b64_tr_b16 v[170:171], v155 offset:0x1400
	ds_read_b64_tr_b16 v[172:173], v155 offset:0x1800
	ds_read_b64_tr_b16 v[174:175], v155 offset:0x1c00
	ds_read_b64_tr_b16 v[160:161], v155 offset:0x200
	ds_read_b64_tr_b16 v[162:163], v155 offset:0x600
	ds_read_b64_tr_b16 v[164:165], v155 offset:0xa00
	ds_read_b64_tr_b16 v[166:167], v155 offset:0xe00
	v_mfma_f32_32x32x16_bf16 v[2:17], v[94:97], v[42:45], v[2:17]
	v_mfma_f32_32x32x16_bf16 v[2:17], v[90:93], v[46:49], v[2:17]
	s_waitcnt lgkmcnt(6)
	v_mfma_f32_32x32x16_bf16 v[2:17], v[86:89], v[168:171], v[2:17]
	ds_read_b64_tr_b16 v[168:169], v155 offset:0x1200
	ds_read_b64_tr_b16 v[170:171], v155 offset:0x1600
	s_waitcnt lgkmcnt(6)
	v_mfma_f32_32x32x16_bf16 v[2:17], v[82:85], v[172:175], v[2:17]
	ds_read_b64_tr_b16 v[176:177], v155 offset:0x1a00
	ds_read_b64_tr_b16 v[178:179], v155 offset:0x1e00
	s_waitcnt lgkmcnt(0)
	v_mfma_f32_32x32x16_bf16 v[18:33], v[94:97], v[160:163], v[18:33]
	s_waitcnt vmcnt(2)
	ds_write_b128 v158, v[138:141] offset:8192
	ds_write_b128 v157, v[142:145] offset:25600
	v_exp_f32_e32 v138, v98
	v_exp_f32_e32 v139, v99
	v_mfma_f32_32x32x16_bf16 v[18:33], v[90:93], v[164:167], v[18:33]
	v_exp_f32_e32 v162, v100
	v_exp_f32_e32 v165, v101
	v_exp_f32_e32 v163, v102
	v_exp_f32_e32 v166, v103
	v_exp_f32_e32 v164, v104
	v_exp_f32_e32 v167, v105
	v_exp_f32_e32 v140, v106
	v_mfma_f32_32x32x16_bf16 v[18:33], v[86:89], v[168:171], v[18:33]
	v_exp_f32_e32 v144, v107
	v_exp_f32_e32 v141, v108
	v_exp_f32_e32 v145, v109
	v_exp_f32_e32 v142, v110
	v_exp_f32_e32 v160, v111
	v_mfma_f32_16x16x32_bf16 v[34:37], v[94:97], v[38:41], v[34:37]
	v_exp_f32_e32 v143, v112
	v_exp_f32_e32 v161, v113
	v_lshl_add_u64 v[148:149], v[148:149], 0, s[18:19]
	v_xor_b32_e32 v158, 0xc000, v158
	v_xor_b32_e32 v159, 0xc000, v159
	v_xor_b32_e32 v155, 0xc000, v155
	s_cmpk_gt_u32 s21, 0x7c
	s_cbranch_scc1 .Ldense_exit
	s_add_i32 s21, s21, 2
	s_waitcnt lgkmcnt(0)
	s_barrier
	v_mfma_f32_16x16x32_bf16 v[34:37], v[90:93], v[38:41], v[34:37]
	v_mfma_f32_16x16x32_bf16 v[34:37], v[86:89], v[38:41], v[34:37]
	v_mfma_f32_32x32x16_bf16 v[18:33], v[82:85], v[176:179], v[18:33]
	v_mfma_f32_16x16x32_bf16 v[34:37], v[82:85], v[38:41], v[34:37]
; #define SBAR() __builtin_amdgcn_sched_barrier(0)
; #define SLOAD(i, k0) do { st_[i].vs = *reinterpret_cast<const bf16x8*>(&Vh[(size_t)((k0) + sr) * LDK + sc]); \
;     st_[i].ks = *reinterpret_cast<const bf16x8*>(&Kh[(size_t)((k0) + sr) * LDK + sc]); \
;     if (DQ == 96) st_[i].kr = *reinterpret_cast<const bf16x8*>(&Kr[(size_t)((k0) + sr2) * 32 + sc2]); } while (0)
; #define SWRITE(b, i) do { *(bf16x8*)(V_lds + (b) * SHM_V + vst0) = st_[i].vs; *(bf16x8*)(K_lds + (b) * SHM_K + kst0) = st_[i].ks; \
;     if (DQ == 96) { if (tid < 256) *(bf16x8*)(K_lds + (b) * SHM_K + kst2) = st_[i].kr; } } while (0)
; #define SWAIT() do { if (DQ == 96) asm volatile("s_waitcnt vmcnt(3)" ::: "memory"); else asm volatile("s_waitcnt vmcnt(2)" ::: "memory"); } while (0)
; #define SLOAD(i, k0) do { st_[i].vs = *reinterpret_cast<const bf16x8*>(&Vh[(size_t)((k0) + sr) * LDK + sc]); \
;     st_[i].ks = *reinterpret_cast<const bf16x8*>(&Kh[(size_t)((k0) + sr) * LDK + sc]); \
;     if (DQ == 96) st_[i].kr = *reinterpret_cast<const bf16x8*>(&Kr[(size_t)((k0) + sr2) * 32 + sc2]); } while (0)
; #define SWRITE(b, i) do { *(bf16x8*)(V_lds + (b) * SHM_V + vst0) = st_[i].vs; *(bf16x8*)(K_lds + (b) * SHM_K + kst0) = st_[i].ks; \
;     if (DQ == 96) { if (tid < 256) *(bf16x8*)(K_lds + (b) * SHM_K + kst2) = st_[i].kr; } } while (0)
; #define SWAIT() do { if (DQ == 96) asm volatile("s_waitcnt vmcnt(3)" ::: "memory"); else asm volatile("s_waitcnt vmcnt(2)" ::: "memory"); } while (0)
; template <int DQ, bool WIN, int LDQ, int LDK> ...
;     ...
;     for (int j = 1; j + 1 < NT; j += 2) {
;         SBAR(); qkt<DQ>(pB0, pB1, K_lds + SHM_K, qr, minit, r32, hi);
;         finish(pA0, pA1); SBAR();
;         SLOAD(SO, KBASE(j + 2)); SBAR();
;         pv(vb0);
;         __syncthreads(); SWAIT(); SWRITE(0, SE);
;         lsum_upd();
;         if (WIN) win_mask(pB0, pB1, qrow - KBASE(j), hi);
;         exp16(pB0);
;         __syncthreads();
;         SBAR(); qkt<DQ>(pA0, pA1, K_lds, qr, minit, r32, hi);
;         finish(pB0, pB1); SBAR();
;         if (j + 3 < NT) SLOAD(SE, KBASE(j + 3)); SBAR();
.LBB0_493:
	ds_read_b64_tr_b16 v[42:43], v159 offset:0
	ds_read_b64_tr_b16 v[44:45], v159 offset:0x400
	ds_read_b64_tr_b16 v[46:47], v159 offset:0x800
	ds_read_b64_tr_b16 v[48:49], v159 offset:0xc00
	ds_read_b128 v[82:85], v156 offset:25600
	ds_read_b128 v[168:171], v156 offset:25632
	ds_read_b128 v[172:175], v156 offset:30208
	ds_read_b128 v[176:179], v156 offset:30240
	v_exp_f32_e32 v81, v81
	v_exp_f32_e32 v146, v66
	s_waitcnt lgkmcnt(3)
	v_mfma_f32_32x32x16_bf16 v[98:113], v[82:85], v[126:129], v[50:65]
	v_exp_f32_e32 v180, v67
	v_exp_f32_e32 v190, v68
	v_exp_f32_e32 v191, v73
	v_exp_f32_e32 v192, v74
	v_exp_f32_e32 v193, v75
	v_exp_f32_e32 v194, v80
	s_waitcnt lgkmcnt(1)
	v_mfma_f32_32x32x16_bf16 v[82:97], v[172:175], v[126:129], v[50:65]
	v_mfma_f32_32x32x16_bf16 v[98:113], v[168:171], v[122:125], v[98:113]
	ds_read_b128 v[168:171], v156 offset:25664
	ds_read_b128 v[172:175], v156 offset:25696
	ds_read_b128 v[182:185], v156 offset:30272
	ds_read_b128 v[186:189], v156 offset:30304
	v_cvt_pk_bf16_f32 v66, v138, v139
	v_cvt_pk_bf16_f32 v67, v162, v165
	v_cvt_pk_bf16_f32 v68, v163, v166
	s_waitcnt lgkmcnt(4)
	v_mfma_f32_32x32x16_bf16 v[82:97], v[176:179], v[122:125], v[82:97]
	v_exp_f32_e32 v176, v69
	v_exp_f32_e32 v177, v70
	v_exp_f32_e32 v178, v71
	v_exp_f32_e32 v179, v72
	v_cvt_pk_bf16_f32 v69, v164, v167
	v_cvt_pk_bf16_f32 v70, v140, v144
	v_cvt_pk_bf16_f32 v71, v141, v145
	s_waitcnt lgkmcnt(3)
	v_mfma_f32_32x32x16_bf16 v[98:113], v[168:171], v[118:121], v[98:113]
	v_exp_f32_e32 v168, v76
	v_exp_f32_e32 v169, v77
	v_exp_f32_e32 v170, v78
	v_exp_f32_e32 v171, v79
	v_cvt_pk_bf16_f32 v72, v142, v160
	v_cvt_pk_bf16_f32 v73, v143, v161
	v_cvt_pk_bf16_f32 v74, v146, v180
	s_waitcnt lgkmcnt(1)
	v_mfma_f32_32x32x16_bf16 v[82:97], v[182:185], v[118:121], v[82:97]
	v_cvt_pk_bf16_f32 v75, v190, v176
	v_cvt_pk_bf16_f32 v76, v177, v178
	v_cvt_pk_bf16_f32 v77, v179, v191
	v_cvt_pk_bf16_f32 v78, v192, v193
	v_cvt_pk_bf16_f32 v79, v168, v169
	v_cvt_pk_bf16_f32 v80, v170, v171
	v_cvt_pk_bf16_f32 v81, v194, v81
	v_mfma_f32_32x32x16_bf16 v[98:113], v[172:175], v[114:117], v[98:113]
	s_waitcnt lgkmcnt(0)
	v_mfma_f32_32x32x16_bf16 v[82:97], v[186:189], v[114:117], v[82:97]
	v_add_co_u32_e32 v142, vcc, s90, v148
	s_nop 1
	v_addc_co_u32_e32 v143, vcc, -1, v149, vcc
	global_load_dwordx4 v[138:141], v[142:143], off
	s_nop 0
	global_load_dwordx4 v[142:145], v[142:143], off offset:-256
	ds_read_b64_tr_b16 v[168:169], v159 offset:0x1000
	ds_read_b64_tr_b16 v[170:171], v159 offset:0x1400
	ds_read_b64_tr_b16 v[172:173], v159 offset:0x1800
	ds_read_b64_tr_b16 v[174:175], v159 offset:0x1c00
	ds_read_b64_tr_b16 v[160:161], v159 offset:0x200
	ds_read_b64_tr_b16 v[162:163], v159 offset:0x600
	ds_read_b64_tr_b16 v[164:165], v159 offset:0xa00
	ds_read_b64_tr_b16 v[166:167], v159 offset:0xe00
	v_mfma_f32_32x32x16_bf16 v[2:17], v[66:69], v[42:45], v[2:17]
	v_mfma_f32_32x32x16_bf16 v[2:17], v[70:73], v[46:49], v[2:17]
	s_waitcnt lgkmcnt(6)
	v_mfma_f32_32x32x16_bf16 v[2:17], v[74:77], v[168:171], v[2:17]
	ds_read_b64_tr_b16 v[168:169], v159 offset:0x1200
	ds_read_b64_tr_b16 v[170:171], v159 offset:0x1600
	s_waitcnt lgkmcnt(6)
	v_mfma_f32_32x32x16_bf16 v[2:17], v[78:81], v[172:175], v[2:17]
	ds_read_b64_tr_b16 v[176:177], v159 offset:0x1a00
	ds_read_b64_tr_b16 v[178:179], v159 offset:0x1e00
	s_waitcnt lgkmcnt(0)
	v_mfma_f32_32x32x16_bf16 v[18:33], v[66:69], v[160:163], v[18:33]
	s_waitcnt vmcnt(2)
	ds_write_b128 v158, v[134:137]
	ds_write_b128 v157, v[130:133] offset:16384
	v_mfma_f32_16x16x32_bf16 v[34:37], v[66:69], v[38:41], v[34:37]
	v_exp_f32_e32 v146, v98
	v_exp_f32_e32 v180, v99
	v_exp_f32_e32 v182, v100
	v_exp_f32_e32 v183, v101
	v_exp_f32_e32 v184, v102
	v_exp_f32_e32 v185, v103
	v_exp_f32_e32 v186, v104
	v_mfma_f32_32x32x16_bf16 v[18:33], v[70:73], v[164:167], v[18:33]
	v_exp_f32_e32 v187, v105
	v_exp_f32_e32 v188, v106
	v_exp_f32_e32 v189, v107
	v_exp_f32_e32 v190, v108
	v_exp_f32_e32 v191, v109
	v_exp_f32_e32 v192, v110
	v_exp_f32_e32 v193, v111
	v_mfma_f32_16x16x32_bf16 v[34:37], v[70:73], v[38:41], v[34:37]
	v_exp_f32_e32 v194, v112
	v_exp_f32_e32 v195, v113
	s_waitcnt lgkmcnt(0)
	s_barrier
	v_mfma_f32_32x32x16_bf16 v[18:33], v[74:77], v[168:171], v[18:33]
	v_mfma_f32_16x16x32_bf16 v[34:37], v[74:77], v[38:41], v[34:37]
	v_mfma_f32_32x32x16_bf16 v[18:33], v[78:81], v[176:179], v[18:33]
	v_mfma_f32_16x16x32_bf16 v[34:37], v[78:81], v[38:41], v[34:37]
	ds_read_b64_tr_b16 v[42:43], v155 offset:0
	ds_read_b64_tr_b16 v[44:45], v155 offset:0x400
	ds_read_b64_tr_b16 v[46:47], v155 offset:0x800
	ds_read_b64_tr_b16 v[48:49], v155 offset:0xc00
	ds_read_b128 v[66:69], v156 offset:16384
	ds_read_b128 v[160:163], v156 offset:16416
	ds_read_b128 v[164:167], v156 offset:20992
	ds_read_b128 v[168:171], v156 offset:21024
	v_exp_f32_e32 v82, v82
	v_exp_f32_e32 v83, v83
	s_waitcnt lgkmcnt(3)
	v_mfma_f32_32x32x16_bf16 v[98:113], v[66:69], v[126:129], v[50:65]
	v_exp_f32_e32 v84, v84
	v_exp_f32_e32 v85, v85
	v_exp_f32_e32 v89, v89
	v_exp_f32_e32 v196, v91
	v_exp_f32_e32 v197, v96
	v_exp_f32_e32 v198, v97
	s_waitcnt lgkmcnt(1)
	v_mfma_f32_32x32x16_bf16 v[66:81], v[164:167], v[126:129], v[50:65]
	v_mfma_f32_32x32x16_bf16 v[98:113], v[160:163], v[122:125], v[98:113]
	ds_read_b128 v[160:163], v156 offset:16448
	ds_read_b128 v[164:167], v156 offset:16480
	ds_read_b128 v[172:175], v156 offset:21056
	ds_read_b128 v[176:179], v156 offset:21088
	s_waitcnt lgkmcnt(4)
	v_mfma_f32_32x32x16_bf16 v[66:81], v[168:171], v[122:125], v[66:81]
	v_exp_f32_e32 v168, v86
	v_exp_f32_e32 v169, v87
	v_exp_f32_e32 v170, v88
	v_exp_f32_e32 v171, v90
	s_waitcnt lgkmcnt(3)
	v_mfma_f32_32x32x16_bf16 v[98:113], v[160:163], v[118:121], v[98:113]
	v_exp_f32_e32 v160, v92
	v_exp_f32_e32 v161, v93
	v_exp_f32_e32 v162, v94
	v_exp_f32_e32 v163, v95
	v_cvt_pk_bf16_f32 v94, v146, v180
	v_cvt_pk_bf16_f32 v95, v182, v183
	v_cvt_pk_bf16_f32 v96, v184, v185
	s_waitcnt lgkmcnt(1)
	v_mfma_f32_32x32x16_bf16 v[66:81], v[172:175], v[118:121], v[66:81]
	v_cvt_pk_bf16_f32 v97, v186, v187
	v_cvt_pk_bf16_f32 v90, v188, v189
	v_cvt_pk_bf16_f32 v91, v190, v191
	v_cvt_pk_bf16_f32 v92, v192, v193
	v_cvt_pk_bf16_f32 v93, v194, v195
	v_cvt_pk_bf16_f32 v86, v82, v83
	v_cvt_pk_bf16_f32 v87, v84, v85
	v_mfma_f32_32x32x16_bf16 v[98:113], v[164:167], v[114:117], v[98:113]
	v_cvt_pk_bf16_f32 v88, v168, v169
	v_cvt_pk_bf16_f32 v89, v170, v89
	v_cvt_pk_bf16_f32 v82, v171, v196
	v_cvt_pk_bf16_f32 v83, v160, v161
	v_cvt_pk_bf16_f32 v84, v162, v163
	v_cvt_pk_bf16_f32 v85, v197, v198
	s_waitcnt lgkmcnt(0)
	v_mfma_f32_32x32x16_bf16 v[66:81], v[176:179], v[114:117], v[66:81]
	global_load_dwordx4 v[134:137], v[148:149], off
	global_load_dwordx4 v[130:133], v[148:149], off offset:-256
	s_branch .LBB0_492
